# SwiGLU epilogue row-rstd cross-lane sums via v_permlane16/32_swap instead of ds_bpermute round trips
# speedup vs baseline: 1.0288x; 1.0044x over previous
; #define WAIT8(a) asm volatile("s_waitcnt vmcnt(0)" : "+v"(a[0]), "+v"(a[1]), "+v"(a[2]), "+v"(a[3]), "+v"(a[4]), "+v"(a[5]), "+v"(a[6]), "+v"(a[7]) :: "memory")
; __device__ __forceinline__ void rows_rstd(const float* SS, int row0, int fq, float (&rs)[2][4]) {
;     ...
;     for (int i = 0; i < 8; ++i) {
;         float s = (p[i].x + p[i].y) + (p[i].z + p[i].w);
;         s += __shfl_xor(s, 16); s += __shfl_xor(s, 32);
;         rs[i >> 2][i & 3] = __builtin_amdgcn_rsqf(s * (1.f / D) + EPS);
;     }
; __device__ __forceinline__ void rows_rstd_finish(f32x4 (&p)[8], float (&rs)[2][4]) {
;     WAIT8(p);
; #pragma unroll
;     for (int i = 0; i < 8; ++i) {
;         float s = (p[i].x + p[i].y) + (p[i].z + p[i].w);
;         s += __shfl_xor(s, 16); s += __shfl_xor(s, 32);
;         rs[i >> 2][i & 3] = __builtin_amdgcn_rsqf(s * (1.f / D) + EPS);
;     }
; }
.LBB0_456:
	v_and_b32_e32 v145, 48, v223
	v_lshl_add_u32 v145, v142, 6, v145
	v_add_u32_e32 v145, 0x20800, v145
	ds_read_b128 v[146:149], v145
	ds_read_b128 v[150:153], v145 offset:1024
	ds_read_b128 v[154:157], v145 offset:2048
	ds_read_b128 v[158:161], v145 offset:3072
	ds_read_b128 v[162:165], v145 offset:8192
	ds_read_b128 v[166:169], v145 offset:9216
	ds_read_b128 v[170:173], v145 offset:10240
	ds_read_b128 v[194:197], v145 offset:11264
	v_pk_mul_f32 v[122:123], v[126:127], v[122:123]
	v_pk_mul_f32 v[120:121], v[124:125], v[120:121]
	v_pk_mul_f32 v[114:115], v[118:119], v[114:115]
	s_waitcnt lgkmcnt(0)
	v_add_f32_e32 v146, v146, v147
	v_add_f32_e32 v150, v150, v151
	v_add_f32_e32 v154, v154, v155
	v_add_f32_e32 v158, v158, v159
	v_add_f32_e32 v162, v162, v163
	v_add_f32_e32 v166, v166, v167
	v_add_f32_e32 v170, v170, v171
	v_add_f32_e32 v194, v194, v195
	v_add_f32_e32 v148, v148, v149
	v_add_f32_e32 v152, v152, v153
	v_add_f32_e32 v156, v156, v157
	v_add_f32_e32 v160, v160, v161
	v_add_f32_e32 v164, v164, v165
	v_add_f32_e32 v168, v168, v169
	v_add_f32_e32 v172, v172, v173
	v_add_f32_e32 v196, v196, v197
	v_add_f32_e32 v146, v146, v148
	v_add_f32_e32 v150, v150, v152
	v_add_f32_e32 v154, v154, v156
	v_add_f32_e32 v158, v158, v160
	v_add_f32_e32 v162, v162, v164
	v_add_f32_e32 v166, v166, v168
	v_add_f32_e32 v170, v170, v172
	v_add_f32_e32 v194, v194, v196
	v_mov_b32_e32 v147, v146
	v_mov_b32_e32 v151, v150
	v_mov_b32_e32 v155, v154
	v_mov_b32_e32 v159, v158
	v_mov_b32_e32 v163, v162
	v_mov_b32_e32 v167, v166
	v_mov_b32_e32 v171, v170
	v_mov_b32_e32 v195, v194
	s_nop 0
	v_permlane16_swap_b32_e32 v146, v147
	v_permlane16_swap_b32_e32 v150, v151
	v_permlane16_swap_b32_e32 v154, v155
	v_permlane16_swap_b32_e32 v158, v159
	v_permlane16_swap_b32_e32 v162, v163
	v_permlane16_swap_b32_e32 v166, v167
	v_permlane16_swap_b32_e32 v170, v171
	v_permlane16_swap_b32_e32 v194, v195
	s_nop 0
	v_add_f32_e32 v146, v146, v147
	v_add_f32_e32 v150, v150, v151
	v_add_f32_e32 v154, v154, v155
	v_add_f32_e32 v158, v158, v159
	v_add_f32_e32 v162, v162, v163
	v_add_f32_e32 v166, v166, v167
	v_add_f32_e32 v170, v170, v171
	v_add_f32_e32 v194, v194, v195
	v_mov_b32_e32 v147, v146
	v_mov_b32_e32 v151, v150
	v_mov_b32_e32 v155, v154
	v_mov_b32_e32 v159, v158
	v_mov_b32_e32 v163, v162
	v_mov_b32_e32 v167, v166
	v_mov_b32_e32 v171, v170
	v_mov_b32_e32 v195, v194
	s_nop 0
	v_permlane32_swap_b32_e32 v146, v147
	v_permlane32_swap_b32_e32 v150, v151
	v_permlane32_swap_b32_e32 v154, v155
	v_permlane32_swap_b32_e32 v158, v159
	v_permlane32_swap_b32_e32 v162, v163
	v_permlane32_swap_b32_e32 v166, v167
	v_permlane32_swap_b32_e32 v170, v171
	v_permlane32_swap_b32_e32 v194, v195
	s_nop 0
	v_add_f32_e32 v146, v146, v147
	v_add_f32_e32 v150, v150, v151
	v_add_f32_e32 v154, v154, v155
	v_add_f32_e32 v158, v158, v159
	v_add_f32_e32 v162, v162, v163
	v_add_f32_e32 v166, v166, v167
	v_add_f32_e32 v170, v170, v171
	v_add_f32_e32 v194, v194, v195
	v_fmamk_f32 v146, v146, 0x3a800000, v220
	v_fmamk_f32 v150, v150, 0x3a800000, v220
	v_fmamk_f32 v154, v154, 0x3a800000, v220
	v_fmamk_f32 v158, v158, 0x3a800000, v220
	v_fmamk_f32 v162, v162, 0x3a800000, v220
	v_fmamk_f32 v166, v166, 0x3a800000, v220
	v_fmamk_f32 v170, v170, 0x3a800000, v220
	v_fmamk_f32 v194, v194, 0x3a800000, v220
	v_rsq_f32_e32 v200, v146
	v_rsq_f32_e32 v242, v150
	v_rsq_f32_e32 v243, v154
	v_rsq_f32_e32 v248, v158
	v_rsq_f32_e32 v249, v162
	v_rsq_f32_e32 v250, v166
	v_rsq_f32_e32 v255, v170
	v_rsq_f32_e32 v192, v194
	s_nop 0
	v_mov_b32_e32 v149, v200
	v_mov_b32_e32 v154, v242
	v_mov_b32_e32 v153, v243
	v_mov_b32_e32 v155, v248
	v_mov_b32_e32 v152, v249
	v_mov_b32_e32 v147, v250
	v_mov_b32_e32 v146, v255
	v_mov_b32_e32 v145, v192
	s_lshl_b32 s11, s50, 4
	s_lshl_b32 s2, s49, 2
	s_add_i32 s11, s11, s47
	s_or_b32 s2, s2, s44
	s_ashr_i32 s3, s2, 31
	s_mul_i32 s13, s11, 0x58
	v_mul_f32_e32 v156, 0xbfb8aa3b, v149
	v_mul_f32_e32 v157, v127, v156
	v_exp_f32_e32 v157, v157
	v_mul_f32_e32 v148, v124, v156
	v_exp_f32_e32 v150, v148
	v_mul_f32_e32 v148, v125, v156
	v_exp_f32_e32 v151, v148
	v_mul_f32_e32 v148, v149, v149
	v_add_f32_e32 v149, 1.0, v150
	v_rcp_f32_e32 v150, v149
	v_add_f32_e32 v149, 1.0, v151
	v_rcp_f32_e32 v151, v149
	v_mul_f32_e32 v149, v126, v156
	v_exp_f32_e32 v149, v149
	v_add_f32_e32 v127, 1.0, v157
	v_rcp_f32_e32 v127, v127
	s_mul_hi_i32 s29, s11, 0x58
	v_add_f32_e32 v126, 1.0, v149
	v_rcp_f32_e32 v126, v126
	v_pk_mul_f32 v[124:125], v[148:149], v[150:151] op_sel_hi:[0,1]
	v_pk_mul_f32 v[120:121], v[120:121], v[124:125]
	s_add_u32 s28, s13, s2
	v_pk_mul_f32 v[124:125], v[148:149], v[126:127] op_sel_hi:[0,1]
	v_mul_f32_e32 v126, v116, v156
	v_mul_f32_e32 v127, v117, v156
	v_exp_f32_e32 v126, v126
	v_exp_f32_e32 v127, v127
	v_pk_mul_f32 v[122:123], v[122:123], v[124:125]
	v_pk_mul_f32 v[112:113], v[116:117], v[112:113]
	v_add_f32_e32 v124, 1.0, v126
	v_add_f32_e32 v125, 1.0, v127
	v_mul_f32_e32 v126, v118, v156
	v_mul_f32_e32 v127, v119, v156
	v_exp_f32_e32 v126, v126
	v_exp_f32_e32 v127, v127
	v_rcp_f32_e32 v124, v124
	v_rcp_f32_e32 v125, v125
	v_add_f32_e32 v118, 1.0, v126
	v_add_f32_e32 v119, 1.0, v127
	v_rcp_f32_e32 v118, v118
	v_rcp_f32_e32 v119, v119
	v_pk_mul_f32 v[116:117], v[148:149], v[124:125] op_sel_hi:[0,1]
	s_addc_u32 s29, s29, s3
	v_pk_mul_f32 v[116:117], v[112:113], v[116:117]
	v_pk_mul_f32 v[112:113], v[148:149], v[118:119] op_sel_hi:[0,1]
	s_lshl_b64 s[28:29], s[28:29], 10
	v_pk_mul_f32 v[118:119], v[114:115], v[112:113]
	v_lshl_add_u64 v[124:125], v[134:135], 0, s[28:29]
	v_cvt_pk_bf16_f32 v112, v120, v121
	v_cvt_pk_bf16_f32 v113, v122, v123
	v_cvt_pk_bf16_f32 v114, v116, v117
; __device__ __forceinline__ unsigned cvtpk(float lo, float hi) { f32x2_t v = {lo, hi}; bf16x2_t b = __builtin_convertvector(v, bf16x2_t); return __builtin_bit_cast(unsigned, b); }
;     __device__ __forceinline__ void operator()(const AccT& acc, const Unit& u, int wr, int wc, int fr, int fq, LAS unsigned char* stg) const {
;     ...
; #pragma unroll
;         for (int ai = 0; ai < 2; ++ai)
; #pragma unroll
;             for (int m = 0; m < 4; ++m) {
;                 bf16_t* rowp = O + ((size_t)(u.pm * 16 + wr * 4 + ai * 8 + m) * (ldo >> 5) + (u.pn * 4 + wc)) * 512 + fr * 32 + 8 * fq;
;                 const float k1 = rs[ai][m] * -1.4426950408889634f, k2 = rs[ai][m] * rs[ai][m];
;                 float r[8];
; #pragma unroll
;                 for (int n = 0; n < 2; ++n)
; #pragma unroll
;                     for (int i = 0; i < 4; ++i) {
;                         const float g = acc[ai][0][m][n][i], up = acc[ai][1][m][n][i];
;                         const float e = __builtin_amdgcn_exp2f(g * k1);
;                         r[n * 4 + i] = (g * up) * (k2 * __builtin_amdgcn_rcpf(1.0f + e));
;                     }
;                 u32x4 w; w.x = cvtpk(r[0], r[1]); w.y = cvtpk(r[2], r[3]); w.z = cvtpk(r[4], r[5]); w.w = cvtpk(r[6], r[7]);
;                 __builtin_nontemporal_store(w, (u32x4*)rowp);
;             }
	v_cvt_pk_bf16_f32 v115, v118, v119
	global_store_dwordx4 v[124:125], v[112:115], off nt
	v_pk_mul_f32 v[106:107], v[110:111], v[106:107]
	v_pk_mul_f32 v[104:105], v[108:109], v[104:105]
	v_mul_f32_e32 v113, 0xbfb8aa3b, v154
	v_mul_f32_e32 v112, v108, v113
	v_exp_f32_e32 v114, v112
	v_mul_f32_e32 v112, v109, v113
	v_exp_f32_e32 v115, v112
	v_mul_f32_e32 v116, v110, v113
	v_mul_f32_e32 v117, v111, v113
	v_exp_f32_e32 v116, v116
	v_exp_f32_e32 v117, v117
	v_add_f32_e32 v114, 1.0, v114
	v_add_f32_e32 v115, 1.0, v115
	v_rcp_f32_e32 v114, v114
	v_rcp_f32_e32 v115, v115
	v_add_f32_e32 v110, 1.0, v116
	v_add_f32_e32 v111, 1.0, v117
	v_rcp_f32_e32 v110, v110
	v_rcp_f32_e32 v111, v111
	v_mul_f32_e32 v112, v154, v154
	v_pk_mul_f32 v[108:109], v[112:113], v[114:115] op_sel_hi:[0,1]
	v_pk_mul_f32 v[104:105], v[104:105], v[108:109]
	v_pk_mul_f32 v[108:109], v[112:113], v[110:111] op_sel_hi:[0,1]
	v_mul_f32_e32 v110, v100, v113
	v_mul_f32_e32 v111, v101, v113
	v_exp_f32_e32 v110, v110
	v_exp_f32_e32 v111, v111
	v_pk_mul_f32 v[106:107], v[106:107], v[108:109]
	v_pk_mul_f32 v[98:99], v[102:103], v[98:99]
	v_add_f32_e32 v108, 1.0, v110
	v_add_f32_e32 v109, 1.0, v111
	v_mul_f32_e32 v110, v102, v113
	v_mul_f32_e32 v111, v103, v113
	v_exp_f32_e32 v110, v110
	v_exp_f32_e32 v111, v111
	v_rcp_f32_e32 v108, v108
	v_rcp_f32_e32 v109, v109
	v_add_f32_e32 v102, 1.0, v110
	v_add_f32_e32 v103, 1.0, v111
	v_rcp_f32_e32 v102, v102
	v_rcp_f32_e32 v103, v103
	s_or_b32 s28, s11, 1
	s_mul_hi_i32 s29, s28, 0x58
	s_mulk_i32 s28, 0x58
	s_add_u32 s28, s28, s2
	v_pk_mul_f32 v[96:97], v[100:101], v[96:97]
	v_pk_mul_f32 v[100:101], v[112:113], v[108:109] op_sel_hi:[0,1]
	s_addc_u32 s29, s29, s3
	v_pk_mul_f32 v[100:101], v[96:97], v[100:101]
	v_pk_mul_f32 v[96:97], v[112:113], v[102:103] op_sel_hi:[0,1]
	s_lshl_b64 s[28:29], s[28:29], 10
	v_pk_mul_f32 v[102:103], v[98:99], v[96:97]
	v_lshl_add_u64 v[108:109], v[134:135], 0, s[28:29]
	v_cvt_pk_bf16_f32 v96, v104, v105
	v_cvt_pk_bf16_f32 v97, v106, v107
	v_cvt_pk_bf16_f32 v98, v100, v101
	v_cvt_pk_bf16_f32 v99, v102, v103
	global_store_dwordx4 v[108:109], v[96:99], off nt
	v_pk_mul_f32 v[90:91], v[94:95], v[90:91]
	v_pk_mul_f32 v[88:89], v[92:93], v[88:89]
	v_mul_f32_e32 v97, 0xbfb8aa3b, v153
	v_mul_f32_e32 v96, v92, v97
	v_exp_f32_e32 v98, v96
	v_mul_f32_e32 v96, v93, v97
	v_exp_f32_e32 v99, v96
	v_mul_f32_e32 v100, v94, v97
	v_mul_f32_e32 v101, v95, v97
	v_exp_f32_e32 v100, v100
	v_exp_f32_e32 v101, v101
	v_add_f32_e32 v98, 1.0, v98
	v_add_f32_e32 v99, 1.0, v99
	v_rcp_f32_e32 v98, v98
	v_rcp_f32_e32 v99, v99
	v_add_f32_e32 v94, 1.0, v100
	v_add_f32_e32 v95, 1.0, v101
	v_rcp_f32_e32 v94, v94
	v_rcp_f32_e32 v95, v95
	v_mul_f32_e32 v96, v153, v153
	v_pk_mul_f32 v[92:93], v[96:97], v[98:99] op_sel_hi:[0,1]
	v_pk_mul_f32 v[88:89], v[88:89], v[92:93]
	v_pk_mul_f32 v[92:93], v[96:97], v[94:95] op_sel_hi:[0,1]
	v_mul_f32_e32 v94, v84, v97
	v_mul_f32_e32 v95, v85, v97
	v_exp_f32_e32 v94, v94
	v_exp_f32_e32 v95, v95
	v_pk_mul_f32 v[90:91], v[90:91], v[92:93]
	v_pk_mul_f32 v[82:83], v[86:87], v[82:83]
	v_add_f32_e32 v92, 1.0, v94
	v_add_f32_e32 v93, 1.0, v95
	v_mul_f32_e32 v94, v86, v97
	v_mul_f32_e32 v95, v87, v97
	v_exp_f32_e32 v94, v94
	v_exp_f32_e32 v95, v95
	v_rcp_f32_e32 v92, v92
	v_rcp_f32_e32 v93, v93
	v_add_f32_e32 v86, 1.0, v94
	v_add_f32_e32 v87, 1.0, v95
	v_rcp_f32_e32 v86, v86
	v_rcp_f32_e32 v87, v87
	s_or_b32 s28, s11, 2
	s_mul_hi_i32 s29, s28, 0x58
	s_mulk_i32 s28, 0x58
	s_add_u32 s28, s28, s2
	v_pk_mul_f32 v[80:81], v[84:85], v[80:81]
	v_pk_mul_f32 v[84:85], v[96:97], v[92:93] op_sel_hi:[0,1]
	s_addc_u32 s29, s29, s3
	v_pk_mul_f32 v[84:85], v[80:81], v[84:85]
	v_pk_mul_f32 v[80:81], v[96:97], v[86:87] op_sel_hi:[0,1]
	s_lshl_b64 s[28:29], s[28:29], 10
	v_pk_mul_f32 v[86:87], v[82:83], v[80:81]
	v_lshl_add_u64 v[92:93], v[134:135], 0, s[28:29]
	v_cvt_pk_bf16_f32 v80, v88, v89
	v_cvt_pk_bf16_f32 v81, v90, v91
	v_cvt_pk_bf16_f32 v82, v84, v85
	v_cvt_pk_bf16_f32 v83, v86, v87
	global_store_dwordx4 v[92:93], v[80:83], off nt
	v_pk_mul_f32 v[74:75], v[78:79], v[74:75]
	v_pk_mul_f32 v[72:73], v[76:77], v[72:73]
	v_mul_f32_e32 v81, 0xbfb8aa3b, v155
	v_mul_f32_e32 v80, v76, v81
	v_exp_f32_e32 v82, v80
	v_mul_f32_e32 v80, v77, v81
	v_exp_f32_e32 v83, v80
	v_mul_f32_e32 v84, v78, v81
	v_mul_f32_e32 v85, v79, v81
	v_exp_f32_e32 v84, v84
	v_exp_f32_e32 v85, v85
	v_add_f32_e32 v82, 1.0, v82
	v_add_f32_e32 v83, 1.0, v83
	v_rcp_f32_e32 v82, v82
	v_rcp_f32_e32 v83, v83
	v_add_f32_e32 v78, 1.0, v84
	v_add_f32_e32 v79, 1.0, v85
	v_rcp_f32_e32 v78, v78
	v_rcp_f32_e32 v79, v79
	v_mul_f32_e32 v80, v155, v155
	v_pk_mul_f32 v[76:77], v[80:81], v[82:83] op_sel_hi:[0,1]
	v_pk_mul_f32 v[72:73], v[72:73], v[76:77]
	v_pk_mul_f32 v[76:77], v[80:81], v[78:79] op_sel_hi:[0,1]
	v_mul_f32_e32 v78, v68, v81
	v_mul_f32_e32 v79, v69, v81
	v_exp_f32_e32 v78, v78
	v_exp_f32_e32 v79, v79
	v_pk_mul_f32 v[74:75], v[74:75], v[76:77]
	v_pk_mul_f32 v[66:67], v[70:71], v[66:67]
	v_add_f32_e32 v76, 1.0, v78
	v_add_f32_e32 v77, 1.0, v79
	v_mul_f32_e32 v78, v70, v81
	v_mul_f32_e32 v79, v71, v81
	v_exp_f32_e32 v78, v78
	v_exp_f32_e32 v79, v79
	v_rcp_f32_e32 v76, v76
	v_rcp_f32_e32 v77, v77
	v_add_f32_e32 v70, 1.0, v78
	v_add_f32_e32 v71, 1.0, v79
	v_rcp_f32_e32 v70, v70
	v_rcp_f32_e32 v71, v71
	s_or_b32 s28, s11, 3
	s_mul_hi_i32 s29, s28, 0x58
	s_mulk_i32 s28, 0x58
	s_add_u32 s28, s28, s2
	v_pk_mul_f32 v[64:65], v[68:69], v[64:65]
	v_pk_mul_f32 v[68:69], v[80:81], v[76:77] op_sel_hi:[0,1]
	s_addc_u32 s29, s29, s3
	v_pk_mul_f32 v[68:69], v[64:65], v[68:69]
	v_pk_mul_f32 v[64:65], v[80:81], v[70:71] op_sel_hi:[0,1]
	s_lshl_b64 s[28:29], s[28:29], 10
	v_pk_mul_f32 v[70:71], v[66:67], v[64:65]
; __device__ __forceinline__ unsigned cvtpk(float lo, float hi) { f32x2_t v = {lo, hi}; bf16x2_t b = __builtin_convertvector(v, bf16x2_t); return __builtin_bit_cast(unsigned, b); }
;     __device__ __forceinline__ void operator()(const AccT& acc, const Unit& u, int wr, int wc, int fr, int fq, LAS unsigned char* stg) const {
;     ...
; #pragma unroll
;         for (int ai = 0; ai < 2; ++ai)
; #pragma unroll
;             for (int m = 0; m < 4; ++m) {
;                 bf16_t* rowp = O + ((size_t)(u.pm * 16 + wr * 4 + ai * 8 + m) * (ldo >> 5) + (u.pn * 4 + wc)) * 512 + fr * 32 + 8 * fq;
;                 const float k1 = rs[ai][m] * -1.4426950408889634f, k2 = rs[ai][m] * rs[ai][m];
;                 float r[8];
; #pragma unroll
;                 for (int n = 0; n < 2; ++n)
; #pragma unroll
;                     for (int i = 0; i < 4; ++i) {
;                         const float g = acc[ai][0][m][n][i], up = acc[ai][1][m][n][i];
;                         const float e = __builtin_amdgcn_exp2f(g * k1);
;                         r[n * 4 + i] = (g * up) * (k2 * __builtin_amdgcn_rcpf(1.0f + e));
;                     }
;                 u32x4 w; w.x = cvtpk(r[0], r[1]); w.y = cvtpk(r[2], r[3]); w.z = cvtpk(r[4], r[5]); w.w = cvtpk(r[6], r[7]);
;                 __builtin_nontemporal_store(w, (u32x4*)rowp);
;             }
	v_lshl_add_u64 v[76:77], v[134:135], 0, s[28:29]
	v_cvt_pk_bf16_f32 v64, v72, v73
	v_cvt_pk_bf16_f32 v65, v74, v75
	v_cvt_pk_bf16_f32 v66, v68, v69
	v_cvt_pk_bf16_f32 v67, v70, v71
	global_store_dwordx4 v[76:77], v[64:67], off nt
	v_pk_mul_f32 v[58:59], v[62:63], v[58:59]
	v_pk_mul_f32 v[56:57], v[60:61], v[56:57]
	v_mul_f32_e32 v65, 0xbfb8aa3b, v152
	v_mul_f32_e32 v64, v60, v65
	v_exp_f32_e32 v66, v64
	v_mul_f32_e32 v64, v61, v65
	v_exp_f32_e32 v67, v64
	v_mul_f32_e32 v68, v62, v65
	v_mul_f32_e32 v69, v63, v65
	v_exp_f32_e32 v68, v68
	v_exp_f32_e32 v69, v69
	v_add_f32_e32 v66, 1.0, v66
	v_add_f32_e32 v67, 1.0, v67
	v_rcp_f32_e32 v66, v66
	v_rcp_f32_e32 v67, v67
	v_add_f32_e32 v62, 1.0, v68
	v_add_f32_e32 v63, 1.0, v69
	v_rcp_f32_e32 v62, v62
	v_rcp_f32_e32 v63, v63
	v_mul_f32_e32 v64, v152, v152
	v_pk_mul_f32 v[60:61], v[64:65], v[66:67] op_sel_hi:[0,1]
	v_pk_mul_f32 v[56:57], v[56:57], v[60:61]
	v_pk_mul_f32 v[60:61], v[64:65], v[62:63] op_sel_hi:[0,1]
	v_mul_f32_e32 v62, v52, v65
	v_mul_f32_e32 v63, v53, v65
	v_exp_f32_e32 v62, v62
	v_exp_f32_e32 v63, v63
	v_pk_mul_f32 v[58:59], v[58:59], v[60:61]
	v_pk_mul_f32 v[50:51], v[54:55], v[50:51]
	v_add_f32_e32 v60, 1.0, v62
	v_add_f32_e32 v61, 1.0, v63
	v_mul_f32_e32 v62, v54, v65
	v_mul_f32_e32 v63, v55, v65
	v_exp_f32_e32 v62, v62
	v_exp_f32_e32 v63, v63
	v_rcp_f32_e32 v60, v60
	v_rcp_f32_e32 v61, v61
	v_add_f32_e32 v54, 1.0, v62
	v_add_f32_e32 v55, 1.0, v63
	v_rcp_f32_e32 v54, v54
	v_rcp_f32_e32 v55, v55
	s_add_i32 s28, s11, 8
	s_mul_hi_i32 s29, s28, 0x58
	s_add_i32 s28, s13, 0x2c0
	s_add_u32 s28, s28, s2
	v_pk_mul_f32 v[48:49], v[52:53], v[48:49]
	v_pk_mul_f32 v[52:53], v[64:65], v[60:61] op_sel_hi:[0,1]
	s_addc_u32 s29, s29, s3
	v_pk_mul_f32 v[52:53], v[48:49], v[52:53]
	v_pk_mul_f32 v[48:49], v[64:65], v[54:55] op_sel_hi:[0,1]
	s_lshl_b64 s[28:29], s[28:29], 10
	v_pk_mul_f32 v[54:55], v[50:51], v[48:49]
	v_lshl_add_u64 v[60:61], v[134:135], 0, s[28:29]
	v_cvt_pk_bf16_f32 v48, v56, v57
	v_cvt_pk_bf16_f32 v49, v58, v59
	v_cvt_pk_bf16_f32 v50, v52, v53
	v_cvt_pk_bf16_f32 v51, v54, v55
	global_store_dwordx4 v[60:61], v[48:51], off nt
	v_pk_mul_f32 v[42:43], v[46:47], v[42:43]
	v_pk_mul_f32 v[40:41], v[44:45], v[40:41]
	v_mul_f32_e32 v49, 0xbfb8aa3b, v147
	v_mul_f32_e32 v48, v44, v49
	v_exp_f32_e32 v50, v48
	v_mul_f32_e32 v48, v45, v49
	v_exp_f32_e32 v51, v48
	v_mul_f32_e32 v52, v46, v49
	v_mul_f32_e32 v53, v47, v49
	v_exp_f32_e32 v52, v52
	v_exp_f32_e32 v53, v53
	v_add_f32_e32 v50, 1.0, v50
	v_add_f32_e32 v51, 1.0, v51
	v_rcp_f32_e32 v50, v50
	v_rcp_f32_e32 v51, v51
	v_add_f32_e32 v46, 1.0, v52
	v_add_f32_e32 v47, 1.0, v53
	v_rcp_f32_e32 v46, v46
	v_rcp_f32_e32 v47, v47
	v_mul_f32_e32 v48, v147, v147
	v_pk_mul_f32 v[44:45], v[48:49], v[50:51] op_sel_hi:[0,1]
	v_pk_mul_f32 v[40:41], v[40:41], v[44:45]
	v_pk_mul_f32 v[44:45], v[48:49], v[46:47] op_sel_hi:[0,1]
	v_mul_f32_e32 v46, v36, v49
	v_mul_f32_e32 v47, v37, v49
	v_exp_f32_e32 v46, v46
	v_exp_f32_e32 v47, v47
	v_pk_mul_f32 v[42:43], v[42:43], v[44:45]
	v_pk_mul_f32 v[34:35], v[38:39], v[34:35]
	v_add_f32_e32 v44, 1.0, v46
	v_add_f32_e32 v45, 1.0, v47
	v_mul_f32_e32 v46, v38, v49
	v_mul_f32_e32 v47, v39, v49
	v_exp_f32_e32 v46, v46
	v_exp_f32_e32 v47, v47
	v_rcp_f32_e32 v44, v44
	v_rcp_f32_e32 v45, v45
	v_add_f32_e32 v38, 1.0, v46
	v_add_f32_e32 v39, 1.0, v47
	v_rcp_f32_e32 v38, v38
	v_rcp_f32_e32 v39, v39
	s_add_i32 s28, s11, 9
	s_mul_hi_i32 s29, s28, 0x58
	s_add_i32 s28, s13, 0x318
	s_add_u32 s28, s28, s2
	v_pk_mul_f32 v[32:33], v[36:37], v[32:33]
	v_pk_mul_f32 v[36:37], v[48:49], v[44:45] op_sel_hi:[0,1]
	s_addc_u32 s29, s29, s3
	v_pk_mul_f32 v[36:37], v[32:33], v[36:37]
	v_pk_mul_f32 v[32:33], v[48:49], v[38:39] op_sel_hi:[0,1]
	s_lshl_b64 s[28:29], s[28:29], 10
	v_pk_mul_f32 v[38:39], v[34:35], v[32:33]
	v_lshl_add_u64 v[44:45], v[134:135], 0, s[28:29]
	v_cvt_pk_bf16_f32 v32, v40, v41
	v_cvt_pk_bf16_f32 v33, v42, v43
	v_cvt_pk_bf16_f32 v34, v36, v37
; __device__ __forceinline__ unsigned cvtpk(float lo, float hi) { f32x2_t v = {lo, hi}; bf16x2_t b = __builtin_convertvector(v, bf16x2_t); return __builtin_bit_cast(unsigned, b); }
; #define PG8_BAR __builtin_amdgcn_s_barrier()
;     __device__ __forceinline__ void operator()(const AccT& acc, const Unit& u, int wr, int wc, int fr, int fq, LAS unsigned char* stg) const {
;     ...
; #pragma unroll
;         for (int ai = 0; ai < 2; ++ai)
; #pragma unroll
;             for (int m = 0; m < 4; ++m) {
;                 bf16_t* rowp = O + ((size_t)(u.pm * 16 + wr * 4 + ai * 8 + m) * (ldo >> 5) + (u.pn * 4 + wc)) * 512 + fr * 32 + 8 * fq;
;                 const float k1 = rs[ai][m] * -1.4426950408889634f, k2 = rs[ai][m] * rs[ai][m];
;                 float r[8];
; #pragma unroll
;                 for (int n = 0; n < 2; ++n)
; #pragma unroll
;                     for (int i = 0; i < 4; ++i) {
;                         const float g = acc[ai][0][m][n][i], up = acc[ai][1][m][n][i];
;                         const float e = __builtin_amdgcn_exp2f(g * k1);
;                         r[n * 4 + i] = (g * up) * (k2 * __builtin_amdgcn_rcpf(1.0f + e));
;                     }
;                 u32x4 w; w.x = cvtpk(r[0], r[1]); w.y = cvtpk(r[2], r[3]); w.z = cvtpk(r[4], r[5]); w.w = cvtpk(r[6], r[7]);
;                 __builtin_nontemporal_store(w, (u32x4*)rowp);
;             }
; template <class Epi>
; __device__ __forceinline__ void gemm_phase(LAS unsigned char* lds, const Gemm g, const StaticOrder& S, const Epi& E, const int tid) {
;     ...
;         if (!has_next) break;
; #pragma unroll
;         for (int a = 0; a < 2; ++a)
; #pragma unroll
;             for (int b = 0; b < 2; ++b)
; #pragma unroll
;                 for (int m = 0; m < 4; ++m)
; #pragma unroll
;                     for (int n = 0; n < 2; ++n) acc[a][b][m][n] = (f32x4){0.f, 0.f, 0.f, 0.f};
;         cur = nxt; cA = nA; cB = nB; ++ui;
;         if (wr == 1) PG8_BAR;
	v_cvt_pk_bf16_f32 v35, v38, v39
	global_store_dwordx4 v[44:45], v[32:35], off nt
	v_pk_mul_f32 v[26:27], v[30:31], v[26:27]
	v_pk_mul_f32 v[24:25], v[28:29], v[24:25]
	v_mul_f32_e32 v33, 0xbfb8aa3b, v146
	v_mul_f32_e32 v32, v28, v33
	v_exp_f32_e32 v34, v32
	v_mul_f32_e32 v32, v29, v33
	v_exp_f32_e32 v35, v32
	v_mul_f32_e32 v36, v30, v33
	v_mul_f32_e32 v37, v31, v33
	v_exp_f32_e32 v36, v36
	v_exp_f32_e32 v37, v37
	v_add_f32_e32 v34, 1.0, v34
	v_add_f32_e32 v35, 1.0, v35
	v_rcp_f32_e32 v34, v34
	v_rcp_f32_e32 v35, v35
	v_add_f32_e32 v30, 1.0, v36
	v_add_f32_e32 v31, 1.0, v37
	v_rcp_f32_e32 v30, v30
	v_rcp_f32_e32 v31, v31
	v_mul_f32_e32 v32, v146, v146
	v_pk_mul_f32 v[28:29], v[32:33], v[34:35] op_sel_hi:[0,1]
	v_pk_mul_f32 v[24:25], v[24:25], v[28:29]
	v_pk_mul_f32 v[28:29], v[32:33], v[30:31] op_sel_hi:[0,1]
	v_mul_f32_e32 v30, v20, v33
	v_mul_f32_e32 v31, v21, v33
	v_exp_f32_e32 v30, v30
	v_exp_f32_e32 v31, v31
	v_pk_mul_f32 v[26:27], v[26:27], v[28:29]
	v_pk_mul_f32 v[18:19], v[22:23], v[18:19]
	v_add_f32_e32 v28, 1.0, v30
	v_add_f32_e32 v29, 1.0, v31
	v_mul_f32_e32 v30, v22, v33
	v_mul_f32_e32 v31, v23, v33
	v_exp_f32_e32 v30, v30
	v_exp_f32_e32 v31, v31
	v_rcp_f32_e32 v28, v28
	v_rcp_f32_e32 v29, v29
	v_add_f32_e32 v22, 1.0, v30
	v_add_f32_e32 v23, 1.0, v31
	v_rcp_f32_e32 v22, v22
	v_rcp_f32_e32 v23, v23
	s_add_i32 s28, s11, 10
	s_mul_hi_i32 s29, s28, 0x58
	s_add_i32 s28, s13, 0x370
	s_add_u32 s28, s28, s2
	v_pk_mul_f32 v[16:17], v[20:21], v[16:17]
	v_pk_mul_f32 v[20:21], v[32:33], v[28:29] op_sel_hi:[0,1]
	s_addc_u32 s29, s29, s3
	v_pk_mul_f32 v[20:21], v[16:17], v[20:21]
	v_pk_mul_f32 v[16:17], v[32:33], v[22:23] op_sel_hi:[0,1]
	s_lshl_b64 s[28:29], s[28:29], 10
	v_pk_mul_f32 v[22:23], v[18:19], v[16:17]
	v_lshl_add_u64 v[28:29], v[134:135], 0, s[28:29]
	v_cvt_pk_bf16_f32 v16, v24, v25
	v_cvt_pk_bf16_f32 v17, v26, v27
	v_cvt_pk_bf16_f32 v18, v20, v21
	v_cvt_pk_bf16_f32 v19, v22, v23
	global_store_dwordx4 v[28:29], v[16:19], off nt
	v_pk_mul_f32 v[10:11], v[14:15], v[10:11]
	v_pk_mul_f32 v[8:9], v[12:13], v[8:9]
	v_mul_f32_e32 v17, 0xbfb8aa3b, v145
	v_mul_f32_e32 v16, v12, v17
	v_exp_f32_e32 v18, v16
	v_mul_f32_e32 v16, v13, v17
	v_exp_f32_e32 v19, v16
	v_mul_f32_e32 v20, v14, v17
	v_mul_f32_e32 v21, v15, v17
	v_exp_f32_e32 v20, v20
	v_exp_f32_e32 v21, v21
	v_add_f32_e32 v18, 1.0, v18
	v_add_f32_e32 v19, 1.0, v19
	v_rcp_f32_e32 v18, v18
	v_rcp_f32_e32 v19, v19
	v_add_f32_e32 v14, 1.0, v20
	v_add_f32_e32 v15, 1.0, v21
	v_rcp_f32_e32 v14, v14
	v_rcp_f32_e32 v15, v15
	v_mul_f32_e32 v16, v145, v145
	v_pk_mul_f32 v[12:13], v[16:17], v[18:19] op_sel_hi:[0,1]
	v_pk_mul_f32 v[8:9], v[8:9], v[12:13]
	v_pk_mul_f32 v[12:13], v[16:17], v[14:15] op_sel_hi:[0,1]
	v_mul_f32_e32 v14, v4, v17
	v_mul_f32_e32 v15, v5, v17
	v_exp_f32_e32 v14, v14
	v_exp_f32_e32 v15, v15
	v_pk_mul_f32 v[10:11], v[10:11], v[12:13]
	v_pk_mul_f32 v[2:3], v[6:7], v[2:3]
	v_add_f32_e32 v12, 1.0, v14
	v_add_f32_e32 v13, 1.0, v15
	v_mul_f32_e32 v14, v6, v17
	v_mul_f32_e32 v15, v7, v17
	v_exp_f32_e32 v14, v14
	v_exp_f32_e32 v15, v15
	v_rcp_f32_e32 v12, v12
	v_rcp_f32_e32 v13, v13
	v_add_f32_e32 v6, 1.0, v14
	v_add_f32_e32 v7, 1.0, v15
	v_rcp_f32_e32 v6, v6
	v_rcp_f32_e32 v7, v7
	s_add_i32 s11, s11, 11
	s_addk_i32 s13, 0x3c8
	s_mul_hi_i32 s11, s11, 0x58
	s_add_u32 s2, s13, s2
	v_pk_mul_f32 v[0:1], v[4:5], v[0:1]
	v_pk_mul_f32 v[4:5], v[16:17], v[12:13] op_sel_hi:[0,1]
	s_addc_u32 s3, s11, s3
	v_pk_mul_f32 v[4:5], v[0:1], v[4:5]
	v_pk_mul_f32 v[0:1], v[16:17], v[6:7] op_sel_hi:[0,1]
	s_lshl_b64 s[2:3], s[2:3], 10
	v_pk_mul_f32 v[6:7], v[2:3], v[0:1]
	v_lshl_add_u64 v[12:13], v[134:135], 0, s[2:3]
	v_cvt_pk_bf16_f32 v0, v8, v9
	v_cvt_pk_bf16_f32 v1, v10, v11
	v_cvt_pk_bf16_f32 v2, v4, v5
	v_cvt_pk_bf16_f32 v3, v6, v7
	s_andn2_b64 vcc, exec, s[4:5]
	s_mov_b64 s[2:3], -1
	global_store_dwordx4 v[12:13], v[0:3], off nt
	s_cbranch_vccnz .LBB0_449
	s_andn2_b64 vcc, exec, s[6:7]
	s_cbranch_vccnz .LBB0_448
	s_barrier
	s_branch .LBB0_448
